# GEMM main loops: k-inner pairs, accumulators ordered n-major (A fragments alternate between two registers)
# speedup vs baseline: 1.0190x; 1.0190x over previous
.LBB0_178:
	s_add_u32 s26, s22, 0xfffc0080
	s_addc_u32 s27, s23, -1
	s_add_i32 s34, 0, 0x10000
	s_cmp_eq_u32 s59, 12
	s_cselect_b32 s31, s9, s27
	s_cselect_b32 s30, s15, s26
	s_cselect_b32 s27, s13, s58
	s_cselect_b32 s26, s56, s57
	s_add_i32 s35, 0, 0x14000
	v_add_u32_e32 v140, s34, v195
	v_add_u32_e32 v166, s35, v195
	ds_read_b128 v[128:131], v140
	ds_read_b128 v[132:135], v140 offset:1024
	ds_read_b128 v[136:139], v140 offset:2048
	ds_read_b128 v[140:143], v140 offset:3072
	ds_read_b128 v[144:147], v166
	ds_read_b128 v[148:151], v166 offset:1024
	ds_read_b128 v[180:183], v166 offset:2048
	ds_read_b128 v[184:187], v166 offset:3072
	v_lshl_add_u64 v[166:167], s[22:23], 0, v[160:161]
	s_add_i32 m0, s49, 0xc000
	ds_read_b128 v[188:191], v200
	ds_read_b128 v[202:205], v200 offset:1024
	ds_read_b128 v[206:209], v200 offset:2048
	ds_read_b128 v[210:213], v200 offset:3072
	ds_read_b128 v[228:231], v200 offset:4096
	ds_read_b128 v[232:235], v200 offset:5120
	ds_read_b128 v[236:239], v200 offset:6144
	ds_read_b128 v[240:243], v200 offset:7168
	global_load_lds_dwordx4 v[166:167], off
	v_lshl_add_u64 v[166:167], s[22:23], 0, v[162:163]
	s_add_i32 m0, s49, 0xe000
	s_nop 0
	global_load_lds_dwordx4 v[166:167], off
	s_waitcnt vmcnt(8)
	s_waitcnt lgkmcnt(0)
	s_barrier
	s_setprio 1
	s_waitcnt lgkmcnt(0)
	v_mfma_f32_16x16x32_bf16 v[124:127], v[128:131], v[188:191], v[124:127]
	v_mfma_f32_16x16x32_bf16 v[124:127], v[132:135], v[202:205], v[124:127]
	v_mfma_f32_16x16x32_bf16 v[112:115], v[128:131], v[206:209], v[112:115]
	v_mfma_f32_16x16x32_bf16 v[112:115], v[132:135], v[210:213], v[112:115]
	v_mfma_f32_16x16x32_bf16 v[96:99], v[128:131], v[228:231], v[96:99]
	v_mfma_f32_16x16x32_bf16 v[96:99], v[132:135], v[232:235], v[96:99]
	v_mfma_f32_16x16x32_bf16 v[80:83], v[128:131], v[236:239], v[80:83]
	v_mfma_f32_16x16x32_bf16 v[80:83], v[132:135], v[240:243], v[80:83]
	v_mfma_f32_16x16x32_bf16 v[120:123], v[136:139], v[188:191], v[120:123]
	v_mfma_f32_16x16x32_bf16 v[120:123], v[140:143], v[202:205], v[120:123]
	v_mfma_f32_16x16x32_bf16 v[104:107], v[136:139], v[206:209], v[104:107]
	v_mfma_f32_16x16x32_bf16 v[104:107], v[140:143], v[210:213], v[104:107]
	v_mfma_f32_16x16x32_bf16 v[88:91], v[136:139], v[228:231], v[88:91]
	v_mfma_f32_16x16x32_bf16 v[88:91], v[140:143], v[232:235], v[88:91]
	v_mfma_f32_16x16x32_bf16 v[72:75], v[136:139], v[236:239], v[72:75]
	v_mfma_f32_16x16x32_bf16 v[72:75], v[140:143], v[240:243], v[72:75]
	s_setprio 0
	s_setprio 1
	v_mfma_f32_16x16x32_bf16 v[116:119], v[144:147], v[188:191], v[116:119]
	v_mfma_f32_16x16x32_bf16 v[116:119], v[148:151], v[202:205], v[116:119]
	v_mfma_f32_16x16x32_bf16 v[100:103], v[144:147], v[206:209], v[100:103]
	v_mfma_f32_16x16x32_bf16 v[100:103], v[148:151], v[210:213], v[100:103]
	v_mfma_f32_16x16x32_bf16 v[84:87], v[144:147], v[228:231], v[84:87]
	v_mfma_f32_16x16x32_bf16 v[84:87], v[148:151], v[232:235], v[84:87]
	v_mfma_f32_16x16x32_bf16 v[68:71], v[144:147], v[236:239], v[68:71]
	v_mfma_f32_16x16x32_bf16 v[68:71], v[148:151], v[240:243], v[68:71]
	v_mfma_f32_16x16x32_bf16 v[108:111], v[180:183], v[188:191], v[108:111]
	v_mfma_f32_16x16x32_bf16 v[108:111], v[184:187], v[202:205], v[108:111]
	v_mfma_f32_16x16x32_bf16 v[92:95], v[180:183], v[206:209], v[92:95]
	v_mfma_f32_16x16x32_bf16 v[92:95], v[184:187], v[210:213], v[92:95]
	v_mfma_f32_16x16x32_bf16 v[76:79], v[180:183], v[228:231], v[76:79]
	v_mfma_f32_16x16x32_bf16 v[76:79], v[184:187], v[232:235], v[76:79]
	v_mfma_f32_16x16x32_bf16 v[64:67], v[180:183], v[236:239], v[64:67]
	v_mfma_f32_16x16x32_bf16 v[64:67], v[184:187], v[240:243], v[64:67]
	s_setprio 0
	s_barrier
	s_add_i32 s34, s34, s45
	v_lshl_add_u64 v[166:167], s[26:27], 0, v[168:169]
	s_mov_b32 m0, s34
	ds_read_b128 v[188:191], v200 offset:16384
	ds_read_b128 v[202:205], v200 offset:17408
	ds_read_b128 v[206:209], v200 offset:18432
	ds_read_b128 v[210:213], v200 offset:19456
	ds_read_b128 v[228:231], v200 offset:20480
	ds_read_b128 v[232:235], v200 offset:21504
	ds_read_b128 v[236:239], v200 offset:22528
	ds_read_b128 v[240:243], v200 offset:23552
	global_load_lds_dwordx4 v[166:167], off
	s_add_i32 m0, s34, 0x2000
	s_add_u32 s36, s26, 0x40000
	v_lshl_add_u64 v[192:193], s[26:27], 0, v[152:153]
	s_addc_u32 s37, s27, 0
	s_add_i32 s34, s35, s45
	global_load_lds_dwordx4 v[192:193], off
	v_lshl_add_u64 v[198:199], s[36:37], 0, v[168:169]
	s_mov_b32 m0, s34
	v_lshl_add_u64 v[214:215], s[30:31], 0, v[154:155]
	global_load_lds_dwordx4 v[198:199], off
	v_lshl_add_u64 v[198:199], s[36:37], 0, v[152:153]
	s_add_i32 m0, s34, 0x2000
	s_nop 0
	global_load_lds_dwordx4 v[198:199], off
	v_lshl_add_u64 v[198:199], s[30:31], 0, v[156:157]
	s_mov_b32 m0, s49
	s_nop 0
	global_load_lds_dwordx4 v[198:199], off
	s_mov_b32 m0, s50
	s_nop 0
	global_load_lds_dwordx4 v[214:215], off
	s_waitcnt vmcnt(8)
	s_waitcnt lgkmcnt(0)
	s_barrier
	s_setprio 1
	s_waitcnt lgkmcnt(0)
	v_mfma_f32_16x16x32_bf16 v[60:63], v[128:131], v[188:191], v[60:63]
	v_mfma_f32_16x16x32_bf16 v[60:63], v[132:135], v[202:205], v[60:63]
	v_mfma_f32_16x16x32_bf16 v[48:51], v[128:131], v[206:209], v[48:51]
	v_mfma_f32_16x16x32_bf16 v[48:51], v[132:135], v[210:213], v[48:51]
	v_mfma_f32_16x16x32_bf16 v[32:35], v[128:131], v[228:231], v[32:35]
	v_mfma_f32_16x16x32_bf16 v[32:35], v[132:135], v[232:235], v[32:35]
	v_mfma_f32_16x16x32_bf16 v[16:19], v[128:131], v[236:239], v[16:19]
	v_mfma_f32_16x16x32_bf16 v[16:19], v[132:135], v[240:243], v[16:19]
	v_mfma_f32_16x16x32_bf16 v[56:59], v[136:139], v[188:191], v[56:59]
	v_mfma_f32_16x16x32_bf16 v[56:59], v[140:143], v[202:205], v[56:59]
	v_mfma_f32_16x16x32_bf16 v[40:43], v[136:139], v[206:209], v[40:43]
	v_mfma_f32_16x16x32_bf16 v[40:43], v[140:143], v[210:213], v[40:43]
	v_mfma_f32_16x16x32_bf16 v[24:27], v[136:139], v[228:231], v[24:27]
	v_mfma_f32_16x16x32_bf16 v[24:27], v[140:143], v[232:235], v[24:27]
	v_mfma_f32_16x16x32_bf16 v[8:11], v[136:139], v[236:239], v[8:11]
	v_mfma_f32_16x16x32_bf16 v[8:11], v[140:143], v[240:243], v[8:11]
	s_setprio 0
	s_setprio 1
	v_mfma_f32_16x16x32_bf16 v[52:55], v[144:147], v[188:191], v[52:55]
	v_mfma_f32_16x16x32_bf16 v[52:55], v[148:151], v[202:205], v[52:55]
	v_mfma_f32_16x16x32_bf16 v[36:39], v[144:147], v[206:209], v[36:39]
	v_mfma_f32_16x16x32_bf16 v[36:39], v[148:151], v[210:213], v[36:39]
	v_mfma_f32_16x16x32_bf16 v[20:23], v[144:147], v[228:231], v[20:23]
	v_mfma_f32_16x16x32_bf16 v[20:23], v[148:151], v[232:235], v[20:23]
	v_mfma_f32_16x16x32_bf16 v[4:7], v[144:147], v[236:239], v[4:7]
	v_mfma_f32_16x16x32_bf16 v[4:7], v[148:151], v[240:243], v[4:7]
	v_mfma_f32_16x16x32_bf16 v[44:47], v[180:183], v[188:191], v[44:47]
	v_mfma_f32_16x16x32_bf16 v[44:47], v[184:187], v[202:205], v[44:47]
	v_mfma_f32_16x16x32_bf16 v[28:31], v[180:183], v[206:209], v[28:31]
	v_mfma_f32_16x16x32_bf16 v[28:31], v[184:187], v[210:213], v[28:31]
	v_mfma_f32_16x16x32_bf16 v[12:15], v[180:183], v[228:231], v[12:15]
	v_mfma_f32_16x16x32_bf16 v[12:15], v[184:187], v[232:235], v[12:15]
	v_mfma_f32_16x16x32_bf16 v[0:3], v[180:183], v[236:239], v[0:3]
	v_mfma_f32_16x16x32_bf16 v[0:3], v[184:187], v[240:243], v[0:3]
	s_setprio 0
	s_barrier
	s_add_i32 s34, 0, 0x18000
	s_add_i32 s35, 0, 0x1c000
	v_add_u32_e32 v140, s34, v195
	v_add_u32_e32 v184, s35, v195
	ds_read_b128 v[128:131], v140
	ds_read_b128 v[132:135], v140 offset:1024
	ds_read_b128 v[136:139], v140 offset:2048
	ds_read_b128 v[140:143], v140 offset:3072
	ds_read_b128 v[144:147], v184
	ds_read_b128 v[148:151], v184 offset:1024
	ds_read_b128 v[180:183], v184 offset:2048
	ds_read_b128 v[184:187], v184 offset:3072
	s_add_u32 s30, s30, 0x40000
	s_addc_u32 s31, s31, 0
	s_mov_b32 m0, s51
	v_lshl_add_u64 v[244:245], s[30:31], 0, v[156:157]
	ds_read_b128 v[188:191], v200 offset:32768
	ds_read_b128 v[202:205], v200 offset:33792
	ds_read_b128 v[206:209], v200 offset:34816
	ds_read_b128 v[210:213], v200 offset:35840
	ds_read_b128 v[228:231], v200 offset:36864
	ds_read_b128 v[232:235], v200 offset:37888
	ds_read_b128 v[236:239], v200 offset:38912
	ds_read_b128 v[240:243], v200 offset:39936
	global_load_lds_dwordx4 v[244:245], off
	v_lshl_add_u64 v[244:245], s[30:31], 0, v[154:155]
	s_mov_b32 m0, s52
	s_nop 0
	global_load_lds_dwordx4 v[244:245], off
	s_waitcnt vmcnt(8)
	s_waitcnt lgkmcnt(0)
	s_barrier
	s_setprio 1
	s_waitcnt lgkmcnt(0)
	v_mfma_f32_16x16x32_bf16 v[124:127], v[128:131], v[188:191], v[124:127]
	v_mfma_f32_16x16x32_bf16 v[124:127], v[132:135], v[202:205], v[124:127]
	v_mfma_f32_16x16x32_bf16 v[112:115], v[128:131], v[206:209], v[112:115]
	v_mfma_f32_16x16x32_bf16 v[112:115], v[132:135], v[210:213], v[112:115]
	v_mfma_f32_16x16x32_bf16 v[96:99], v[128:131], v[228:231], v[96:99]
	v_mfma_f32_16x16x32_bf16 v[96:99], v[132:135], v[232:235], v[96:99]
	v_mfma_f32_16x16x32_bf16 v[80:83], v[128:131], v[236:239], v[80:83]
	v_mfma_f32_16x16x32_bf16 v[80:83], v[132:135], v[240:243], v[80:83]
	v_mfma_f32_16x16x32_bf16 v[120:123], v[136:139], v[188:191], v[120:123]
	v_mfma_f32_16x16x32_bf16 v[120:123], v[140:143], v[202:205], v[120:123]
	v_mfma_f32_16x16x32_bf16 v[104:107], v[136:139], v[206:209], v[104:107]
	v_mfma_f32_16x16x32_bf16 v[104:107], v[140:143], v[210:213], v[104:107]
	v_mfma_f32_16x16x32_bf16 v[88:91], v[136:139], v[228:231], v[88:91]
	v_mfma_f32_16x16x32_bf16 v[88:91], v[140:143], v[232:235], v[88:91]
	v_mfma_f32_16x16x32_bf16 v[72:75], v[136:139], v[236:239], v[72:75]
	v_mfma_f32_16x16x32_bf16 v[72:75], v[140:143], v[240:243], v[72:75]
	s_setprio 0
	s_setprio 1
	v_mfma_f32_16x16x32_bf16 v[116:119], v[144:147], v[188:191], v[116:119]
	v_mfma_f32_16x16x32_bf16 v[116:119], v[148:151], v[202:205], v[116:119]
	v_mfma_f32_16x16x32_bf16 v[100:103], v[144:147], v[206:209], v[100:103]
	v_mfma_f32_16x16x32_bf16 v[100:103], v[148:151], v[210:213], v[100:103]
	v_mfma_f32_16x16x32_bf16 v[84:87], v[144:147], v[228:231], v[84:87]
	v_mfma_f32_16x16x32_bf16 v[84:87], v[148:151], v[232:235], v[84:87]
	v_mfma_f32_16x16x32_bf16 v[68:71], v[144:147], v[236:239], v[68:71]
	v_mfma_f32_16x16x32_bf16 v[68:71], v[148:151], v[240:243], v[68:71]
	v_mfma_f32_16x16x32_bf16 v[108:111], v[180:183], v[188:191], v[108:111]
	v_mfma_f32_16x16x32_bf16 v[108:111], v[184:187], v[202:205], v[108:111]
	v_mfma_f32_16x16x32_bf16 v[92:95], v[180:183], v[206:209], v[92:95]
	v_mfma_f32_16x16x32_bf16 v[92:95], v[184:187], v[210:213], v[92:95]
	v_mfma_f32_16x16x32_bf16 v[76:79], v[180:183], v[228:231], v[76:79]
	v_mfma_f32_16x16x32_bf16 v[76:79], v[184:187], v[232:235], v[76:79]
	v_mfma_f32_16x16x32_bf16 v[64:67], v[180:183], v[236:239], v[64:67]
	v_mfma_f32_16x16x32_bf16 v[64:67], v[184:187], v[240:243], v[64:67]
	s_setprio 0
	s_barrier
	s_add_i32 s30, s34, s45
	v_lshl_add_u64 v[166:167], v[166:167], 0, s[20:21]
	s_mov_b32 m0, s30
	ds_read_b128 v[188:191], v200 offset:49152
	ds_read_b128 v[202:205], v200 offset:50176
	ds_read_b128 v[206:209], v200 offset:51200
	ds_read_b128 v[210:213], v200 offset:52224
	ds_read_b128 v[228:231], v200 offset:53248
	ds_read_b128 v[232:235], v200 offset:54272
	ds_read_b128 v[236:239], v200 offset:55296
	ds_read_b128 v[240:243], v200 offset:56320
	global_load_lds_dwordx4 v[166:167], off
	s_add_i32 m0, s30, 0x2000
	s_add_u32 s26, s26, 0x40080
	v_lshl_add_u64 v[166:167], v[192:193], 0, s[20:21]
	s_addc_u32 s27, s27, 0
	s_add_i32 s30, s35, s45
	global_load_lds_dwordx4 v[166:167], off
	v_lshl_add_u64 v[166:167], s[26:27], 0, v[168:169]
	s_mov_b32 m0, s30
	s_nop 0
	global_load_lds_dwordx4 v[166:167], off
	v_lshl_add_u64 v[166:167], s[26:27], 0, v[152:153]
	s_add_i32 m0, s30, 0x2000
	s_nop 0
	global_load_lds_dwordx4 v[166:167], off
	v_lshl_add_u64 v[166:167], v[198:199], 0, s[20:21]
	s_mov_b32 m0, s24
	s_nop 0
	global_load_lds_dwordx4 v[166:167], off
	v_lshl_add_u64 v[166:167], v[214:215], 0, s[20:21]
	s_mov_b32 m0, s53
	s_nop 0
	global_load_lds_dwordx4 v[166:167], off
	s_waitcnt vmcnt(8)
	s_waitcnt lgkmcnt(0)
	s_barrier
	s_setprio 1
	s_waitcnt lgkmcnt(0)
	v_mfma_f32_16x16x32_bf16 v[60:63], v[128:131], v[188:191], v[60:63]
	v_mfma_f32_16x16x32_bf16 v[60:63], v[132:135], v[202:205], v[60:63]
	v_mfma_f32_16x16x32_bf16 v[48:51], v[128:131], v[206:209], v[48:51]
	v_mfma_f32_16x16x32_bf16 v[48:51], v[132:135], v[210:213], v[48:51]
	v_mfma_f32_16x16x32_bf16 v[32:35], v[128:131], v[228:231], v[32:35]
	v_mfma_f32_16x16x32_bf16 v[32:35], v[132:135], v[232:235], v[32:35]
	v_mfma_f32_16x16x32_bf16 v[16:19], v[128:131], v[236:239], v[16:19]
	v_mfma_f32_16x16x32_bf16 v[16:19], v[132:135], v[240:243], v[16:19]
	v_mfma_f32_16x16x32_bf16 v[56:59], v[136:139], v[188:191], v[56:59]
	v_mfma_f32_16x16x32_bf16 v[56:59], v[140:143], v[202:205], v[56:59]
	v_mfma_f32_16x16x32_bf16 v[40:43], v[136:139], v[206:209], v[40:43]
	v_mfma_f32_16x16x32_bf16 v[40:43], v[140:143], v[210:213], v[40:43]
	v_mfma_f32_16x16x32_bf16 v[24:27], v[136:139], v[228:231], v[24:27]
	v_mfma_f32_16x16x32_bf16 v[24:27], v[140:143], v[232:235], v[24:27]
	v_mfma_f32_16x16x32_bf16 v[8:11], v[136:139], v[236:239], v[8:11]
	v_mfma_f32_16x16x32_bf16 v[8:11], v[140:143], v[240:243], v[8:11]
	s_setprio 0
	s_setprio 1
	v_mfma_f32_16x16x32_bf16 v[52:55], v[144:147], v[188:191], v[52:55]
	v_mfma_f32_16x16x32_bf16 v[52:55], v[148:151], v[202:205], v[52:55]
	v_mfma_f32_16x16x32_bf16 v[36:39], v[144:147], v[206:209], v[36:39]
	v_mfma_f32_16x16x32_bf16 v[36:39], v[148:151], v[210:213], v[36:39]
	v_mfma_f32_16x16x32_bf16 v[20:23], v[144:147], v[228:231], v[20:23]
	v_mfma_f32_16x16x32_bf16 v[20:23], v[148:151], v[232:235], v[20:23]
	v_mfma_f32_16x16x32_bf16 v[4:7], v[144:147], v[236:239], v[4:7]
	v_mfma_f32_16x16x32_bf16 v[4:7], v[148:151], v[240:243], v[4:7]
	v_mfma_f32_16x16x32_bf16 v[44:47], v[180:183], v[188:191], v[44:47]
	v_mfma_f32_16x16x32_bf16 v[44:47], v[184:187], v[202:205], v[44:47]
	v_mfma_f32_16x16x32_bf16 v[28:31], v[180:183], v[206:209], v[28:31]
	v_mfma_f32_16x16x32_bf16 v[28:31], v[184:187], v[210:213], v[28:31]
	v_mfma_f32_16x16x32_bf16 v[12:15], v[180:183], v[228:231], v[12:15]
	v_mfma_f32_16x16x32_bf16 v[12:15], v[184:187], v[232:235], v[12:15]
	v_mfma_f32_16x16x32_bf16 v[0:3], v[180:183], v[236:239], v[0:3]
	v_mfma_f32_16x16x32_bf16 v[0:3], v[184:187], v[240:243], v[0:3]
	s_setprio 0
	s_barrier
	s_add_i32 s59, s59, 2
	s_add_u32 s22, s22, 0x100
	s_addc_u32 s23, s23, 0
	s_add_u32 s57, s57, 0x100
	s_addc_u32 s58, s58, 0
	s_cmp_gt_u32 s59, 13
	s_cbranch_scc0 .LBB0_178
	s_and_b64 vcc, exec, s[10:11]
	s_cbranch_vccz .LBB0_181
	s_barrier

.LBB0_776:
	s_add_u32 s26, s22, 0xfffc0080
	s_addc_u32 s27, s23, -1
	s_add_i32 s36, 0, 0x10000
	s_cmp_eq_u32 s55, 12
	s_cselect_b32 s31, s15, s27
	s_cselect_b32 s30, s51, s26
	s_cselect_b32 s27, s13, s54
	s_cselect_b32 s26, s52, s53
	s_add_i32 s56, 0, 0x14000
	v_add_u32_e32 v140, s36, v204
	v_add_u32_e32 v156, s56, v204
	ds_read_b128 v[128:131], v140
	ds_read_b128 v[132:135], v140 offset:1024
	ds_read_b128 v[136:139], v140 offset:2048
	ds_read_b128 v[140:143], v140 offset:3072
	ds_read_b128 v[144:147], v156
	ds_read_b128 v[148:151], v156 offset:1024
	ds_read_b128 v[152:155], v156 offset:2048
	ds_read_b128 v[156:159], v156 offset:3072
	v_lshl_add_u64 v[202:203], s[22:23], 0, v[166:167]
	s_add_i32 m0, s42, 0xc000
	ds_read_b128 v[182:185], v206
	ds_read_b128 v[186:189], v206 offset:1024
	ds_read_b128 v[190:193], v206 offset:2048
	ds_read_b128 v[194:197], v206 offset:3072
	ds_read_b128 v[198:201], v206 offset:4096
	ds_read_b128 v[208:211], v206 offset:5120
	ds_read_b128 v[212:215], v206 offset:6144
	ds_read_b128 v[228:231], v206 offset:7168
	global_load_lds_dwordx4 v[202:203], off
	v_lshl_add_u64 v[202:203], s[22:23], 0, v[180:181]
	s_add_i32 m0, s42, 0xe000
	s_nop 0
	global_load_lds_dwordx4 v[202:203], off
	s_waitcnt vmcnt(8)
	s_waitcnt lgkmcnt(0)
	s_barrier
	s_setprio 1
	s_waitcnt lgkmcnt(0)
	v_mfma_f32_16x16x32_bf16 v[124:127], v[128:131], v[182:185], v[124:127]
	v_mfma_f32_16x16x32_bf16 v[124:127], v[132:135], v[186:189], v[124:127]
	v_mfma_f32_16x16x32_bf16 v[108:111], v[128:131], v[190:193], v[108:111]
	v_mfma_f32_16x16x32_bf16 v[108:111], v[132:135], v[194:197], v[108:111]
	v_mfma_f32_16x16x32_bf16 v[92:95], v[128:131], v[198:201], v[92:95]
	v_mfma_f32_16x16x32_bf16 v[92:95], v[132:135], v[208:211], v[92:95]
	v_mfma_f32_16x16x32_bf16 v[76:79], v[128:131], v[212:215], v[76:79]
	v_mfma_f32_16x16x32_bf16 v[76:79], v[132:135], v[228:231], v[76:79]
	v_mfma_f32_16x16x32_bf16 v[120:123], v[136:139], v[182:185], v[120:123]
	v_mfma_f32_16x16x32_bf16 v[120:123], v[140:143], v[186:189], v[120:123]
	v_mfma_f32_16x16x32_bf16 v[104:107], v[136:139], v[190:193], v[104:107]
	v_mfma_f32_16x16x32_bf16 v[104:107], v[140:143], v[194:197], v[104:107]
	v_mfma_f32_16x16x32_bf16 v[88:91], v[136:139], v[198:201], v[88:91]
	v_mfma_f32_16x16x32_bf16 v[88:91], v[140:143], v[208:211], v[88:91]
	v_mfma_f32_16x16x32_bf16 v[72:75], v[136:139], v[212:215], v[72:75]
	v_mfma_f32_16x16x32_bf16 v[72:75], v[140:143], v[228:231], v[72:75]
	s_setprio 0
	s_setprio 1
	v_mfma_f32_16x16x32_bf16 v[116:119], v[144:147], v[182:185], v[116:119]
	v_mfma_f32_16x16x32_bf16 v[116:119], v[148:151], v[186:189], v[116:119]
	v_mfma_f32_16x16x32_bf16 v[100:103], v[144:147], v[190:193], v[100:103]
	v_mfma_f32_16x16x32_bf16 v[100:103], v[148:151], v[194:197], v[100:103]
	v_mfma_f32_16x16x32_bf16 v[84:87], v[144:147], v[198:201], v[84:87]
	v_mfma_f32_16x16x32_bf16 v[84:87], v[148:151], v[208:211], v[84:87]
	v_mfma_f32_16x16x32_bf16 v[68:71], v[144:147], v[212:215], v[68:71]
	v_mfma_f32_16x16x32_bf16 v[68:71], v[148:151], v[228:231], v[68:71]
	v_mfma_f32_16x16x32_bf16 v[112:115], v[152:155], v[182:185], v[112:115]
	v_mfma_f32_16x16x32_bf16 v[112:115], v[156:159], v[186:189], v[112:115]
	v_mfma_f32_16x16x32_bf16 v[96:99], v[152:155], v[190:193], v[96:99]
	v_mfma_f32_16x16x32_bf16 v[96:99], v[156:159], v[194:197], v[96:99]
	v_mfma_f32_16x16x32_bf16 v[80:83], v[152:155], v[198:201], v[80:83]
	v_mfma_f32_16x16x32_bf16 v[80:83], v[156:159], v[208:211], v[80:83]
	v_mfma_f32_16x16x32_bf16 v[64:67], v[152:155], v[212:215], v[64:67]
	v_mfma_f32_16x16x32_bf16 v[64:67], v[156:159], v[228:231], v[64:67]
	s_setprio 0
	s_barrier
	s_add_i32 s36, s36, s35
	v_lshl_add_u64 v[202:203], s[26:27], 0, v[168:169]
	s_mov_b32 m0, s36
	ds_read_b128 v[182:185], v206 offset:16384
	ds_read_b128 v[186:189], v206 offset:17408
	ds_read_b128 v[190:193], v206 offset:18432
	ds_read_b128 v[194:197], v206 offset:19456
	ds_read_b128 v[198:201], v206 offset:20480
	ds_read_b128 v[208:211], v206 offset:21504
	ds_read_b128 v[212:215], v206 offset:22528
	ds_read_b128 v[228:231], v206 offset:23552
	global_load_lds_dwordx4 v[202:203], off
	s_add_i32 m0, s36, 0x2000
	s_add_u32 s36, s26, 0x40000
	v_lshl_add_u64 v[232:233], s[26:27], 0, v[160:161]
	s_addc_u32 s37, s27, 0
	s_add_i32 s56, s56, s35
	global_load_lds_dwordx4 v[232:233], off
	v_lshl_add_u64 v[234:235], s[36:37], 0, v[168:169]
	s_mov_b32 m0, s56
	v_lshl_add_u64 v[236:237], s[30:31], 0, v[162:163]
	global_load_lds_dwordx4 v[234:235], off
	v_lshl_add_u64 v[234:235], s[36:37], 0, v[160:161]
	s_add_i32 m0, s56, 0x2000
	s_nop 0
	global_load_lds_dwordx4 v[234:235], off
	v_lshl_add_u64 v[234:235], s[30:31], 0, v[164:165]
	s_mov_b32 m0, s42
	s_nop 0
	global_load_lds_dwordx4 v[234:235], off
	s_mov_b32 m0, s43
	s_nop 0
	global_load_lds_dwordx4 v[236:237], off
	s_waitcnt vmcnt(8)
	s_waitcnt lgkmcnt(0)
	s_barrier
	s_setprio 1
	s_waitcnt lgkmcnt(0)
	v_mfma_f32_16x16x32_bf16 v[60:63], v[128:131], v[182:185], v[60:63]
	v_mfma_f32_16x16x32_bf16 v[60:63], v[132:135], v[186:189], v[60:63]
	v_mfma_f32_16x16x32_bf16 v[44:47], v[128:131], v[190:193], v[44:47]
	v_mfma_f32_16x16x32_bf16 v[44:47], v[132:135], v[194:197], v[44:47]
	v_mfma_f32_16x16x32_bf16 v[28:31], v[128:131], v[198:201], v[28:31]
	v_mfma_f32_16x16x32_bf16 v[28:31], v[132:135], v[208:211], v[28:31]
	v_mfma_f32_16x16x32_bf16 v[12:15], v[128:131], v[212:215], v[12:15]
	v_mfma_f32_16x16x32_bf16 v[12:15], v[132:135], v[228:231], v[12:15]
	v_mfma_f32_16x16x32_bf16 v[56:59], v[136:139], v[182:185], v[56:59]
	v_mfma_f32_16x16x32_bf16 v[56:59], v[140:143], v[186:189], v[56:59]
	v_mfma_f32_16x16x32_bf16 v[40:43], v[136:139], v[190:193], v[40:43]
	v_mfma_f32_16x16x32_bf16 v[40:43], v[140:143], v[194:197], v[40:43]
	v_mfma_f32_16x16x32_bf16 v[24:27], v[136:139], v[198:201], v[24:27]
	v_mfma_f32_16x16x32_bf16 v[24:27], v[140:143], v[208:211], v[24:27]
	v_mfma_f32_16x16x32_bf16 v[8:11], v[136:139], v[212:215], v[8:11]
	v_mfma_f32_16x16x32_bf16 v[8:11], v[140:143], v[228:231], v[8:11]
	s_setprio 0
	s_setprio 1
	v_mfma_f32_16x16x32_bf16 v[52:55], v[144:147], v[182:185], v[52:55]
	v_mfma_f32_16x16x32_bf16 v[52:55], v[148:151], v[186:189], v[52:55]
	v_mfma_f32_16x16x32_bf16 v[36:39], v[144:147], v[190:193], v[36:39]
	v_mfma_f32_16x16x32_bf16 v[36:39], v[148:151], v[194:197], v[36:39]
	v_mfma_f32_16x16x32_bf16 v[20:23], v[144:147], v[198:201], v[20:23]
	v_mfma_f32_16x16x32_bf16 v[20:23], v[148:151], v[208:211], v[20:23]
	v_mfma_f32_16x16x32_bf16 v[4:7], v[144:147], v[212:215], v[4:7]
	v_mfma_f32_16x16x32_bf16 v[4:7], v[148:151], v[228:231], v[4:7]
	v_mfma_f32_16x16x32_bf16 v[48:51], v[152:155], v[182:185], v[48:51]
	v_mfma_f32_16x16x32_bf16 v[48:51], v[156:159], v[186:189], v[48:51]
	v_mfma_f32_16x16x32_bf16 v[32:35], v[152:155], v[190:193], v[32:35]
	v_mfma_f32_16x16x32_bf16 v[32:35], v[156:159], v[194:197], v[32:35]
	v_mfma_f32_16x16x32_bf16 v[16:19], v[152:155], v[198:201], v[16:19]
	v_mfma_f32_16x16x32_bf16 v[16:19], v[156:159], v[208:211], v[16:19]
	v_mfma_f32_16x16x32_bf16 v[0:3], v[152:155], v[212:215], v[0:3]
	v_mfma_f32_16x16x32_bf16 v[0:3], v[156:159], v[228:231], v[0:3]
	s_setprio 0
	s_barrier
	s_add_i32 s36, 0, 0x18000
	s_add_i32 s37, 0, 0x1c000
	v_add_u32_e32 v140, s36, v204
	v_add_u32_e32 v156, s37, v204
	ds_read_b128 v[128:131], v140
	ds_read_b128 v[132:135], v140 offset:1024
	ds_read_b128 v[136:139], v140 offset:2048
	ds_read_b128 v[140:143], v140 offset:3072
	ds_read_b128 v[144:147], v156
	ds_read_b128 v[148:151], v156 offset:1024
	ds_read_b128 v[152:155], v156 offset:2048
	ds_read_b128 v[156:159], v156 offset:3072
	s_add_u32 s30, s30, 0x40000
	s_addc_u32 s31, s31, 0
	s_mov_b32 m0, s44
	v_lshl_add_u64 v[238:239], s[30:31], 0, v[164:165]
	ds_read_b128 v[182:185], v206 offset:32768
	ds_read_b128 v[186:189], v206 offset:33792
	ds_read_b128 v[190:193], v206 offset:34816
	ds_read_b128 v[194:197], v206 offset:35840
	ds_read_b128 v[198:201], v206 offset:36864
	ds_read_b128 v[208:211], v206 offset:37888
	ds_read_b128 v[212:215], v206 offset:38912
	ds_read_b128 v[228:231], v206 offset:39936
	global_load_lds_dwordx4 v[238:239], off
	v_lshl_add_u64 v[238:239], s[30:31], 0, v[162:163]
	s_mov_b32 m0, s45
	s_nop 0
	global_load_lds_dwordx4 v[238:239], off
	s_waitcnt vmcnt(8)
	s_waitcnt lgkmcnt(0)
	s_barrier
	s_setprio 1
	s_waitcnt lgkmcnt(0)
	v_mfma_f32_16x16x32_bf16 v[124:127], v[128:131], v[182:185], v[124:127]
	v_mfma_f32_16x16x32_bf16 v[124:127], v[132:135], v[186:189], v[124:127]
	v_mfma_f32_16x16x32_bf16 v[108:111], v[128:131], v[190:193], v[108:111]
	v_mfma_f32_16x16x32_bf16 v[108:111], v[132:135], v[194:197], v[108:111]
	v_mfma_f32_16x16x32_bf16 v[92:95], v[128:131], v[198:201], v[92:95]
	v_mfma_f32_16x16x32_bf16 v[92:95], v[132:135], v[208:211], v[92:95]
	v_mfma_f32_16x16x32_bf16 v[76:79], v[128:131], v[212:215], v[76:79]
	v_mfma_f32_16x16x32_bf16 v[76:79], v[132:135], v[228:231], v[76:79]
	v_mfma_f32_16x16x32_bf16 v[120:123], v[136:139], v[182:185], v[120:123]
	v_mfma_f32_16x16x32_bf16 v[120:123], v[140:143], v[186:189], v[120:123]
	v_mfma_f32_16x16x32_bf16 v[104:107], v[136:139], v[190:193], v[104:107]
	v_mfma_f32_16x16x32_bf16 v[104:107], v[140:143], v[194:197], v[104:107]
	v_mfma_f32_16x16x32_bf16 v[88:91], v[136:139], v[198:201], v[88:91]
	v_mfma_f32_16x16x32_bf16 v[88:91], v[140:143], v[208:211], v[88:91]
	v_mfma_f32_16x16x32_bf16 v[72:75], v[136:139], v[212:215], v[72:75]
	v_mfma_f32_16x16x32_bf16 v[72:75], v[140:143], v[228:231], v[72:75]
	s_setprio 0
	s_setprio 1
	v_mfma_f32_16x16x32_bf16 v[116:119], v[144:147], v[182:185], v[116:119]
	v_mfma_f32_16x16x32_bf16 v[116:119], v[148:151], v[186:189], v[116:119]
	v_mfma_f32_16x16x32_bf16 v[100:103], v[144:147], v[190:193], v[100:103]
	v_mfma_f32_16x16x32_bf16 v[100:103], v[148:151], v[194:197], v[100:103]
	v_mfma_f32_16x16x32_bf16 v[84:87], v[144:147], v[198:201], v[84:87]
	v_mfma_f32_16x16x32_bf16 v[84:87], v[148:151], v[208:211], v[84:87]
	v_mfma_f32_16x16x32_bf16 v[68:71], v[144:147], v[212:215], v[68:71]
	v_mfma_f32_16x16x32_bf16 v[68:71], v[148:151], v[228:231], v[68:71]
	v_mfma_f32_16x16x32_bf16 v[112:115], v[152:155], v[182:185], v[112:115]
	v_mfma_f32_16x16x32_bf16 v[112:115], v[156:159], v[186:189], v[112:115]
	v_mfma_f32_16x16x32_bf16 v[96:99], v[152:155], v[190:193], v[96:99]
	v_mfma_f32_16x16x32_bf16 v[96:99], v[156:159], v[194:197], v[96:99]
	v_mfma_f32_16x16x32_bf16 v[80:83], v[152:155], v[198:201], v[80:83]
	v_mfma_f32_16x16x32_bf16 v[80:83], v[156:159], v[208:211], v[80:83]
	v_mfma_f32_16x16x32_bf16 v[64:67], v[152:155], v[212:215], v[64:67]
	v_mfma_f32_16x16x32_bf16 v[64:67], v[156:159], v[228:231], v[64:67]
	s_setprio 0
	s_barrier
	s_add_i32 s30, s36, s35
	v_lshl_add_u64 v[202:203], v[202:203], 0, s[20:21]
	s_mov_b32 m0, s30
	ds_read_b128 v[182:185], v206 offset:49152
	ds_read_b128 v[186:189], v206 offset:50176
	ds_read_b128 v[190:193], v206 offset:51200
	ds_read_b128 v[194:197], v206 offset:52224
	ds_read_b128 v[198:201], v206 offset:53248
	ds_read_b128 v[208:211], v206 offset:54272
	ds_read_b128 v[212:215], v206 offset:55296
	ds_read_b128 v[228:231], v206 offset:56320
	global_load_lds_dwordx4 v[202:203], off
	s_add_i32 m0, s30, 0x2000
	s_add_u32 s26, s26, 0x40080
	v_lshl_add_u64 v[202:203], v[232:233], 0, s[20:21]
	s_addc_u32 s27, s27, 0
	s_add_i32 s30, s37, s35
	global_load_lds_dwordx4 v[202:203], off
	v_lshl_add_u64 v[202:203], s[26:27], 0, v[168:169]
	s_mov_b32 m0, s30
	s_nop 0
	global_load_lds_dwordx4 v[202:203], off
	v_lshl_add_u64 v[202:203], s[26:27], 0, v[160:161]
	s_add_i32 m0, s30, 0x2000
	s_nop 0
	global_load_lds_dwordx4 v[202:203], off
	v_lshl_add_u64 v[202:203], v[234:235], 0, s[20:21]
	s_mov_b32 m0, s47
	s_nop 0
	global_load_lds_dwordx4 v[202:203], off
	v_lshl_add_u64 v[202:203], v[236:237], 0, s[20:21]
	s_mov_b32 m0, s48
	s_nop 0
	global_load_lds_dwordx4 v[202:203], off
	s_waitcnt vmcnt(8)
	s_waitcnt lgkmcnt(0)
	s_barrier
	s_setprio 1
	s_waitcnt lgkmcnt(0)
	v_mfma_f32_16x16x32_bf16 v[60:63], v[128:131], v[182:185], v[60:63]
	v_mfma_f32_16x16x32_bf16 v[60:63], v[132:135], v[186:189], v[60:63]
	v_mfma_f32_16x16x32_bf16 v[44:47], v[128:131], v[190:193], v[44:47]
	v_mfma_f32_16x16x32_bf16 v[44:47], v[132:135], v[194:197], v[44:47]
	v_mfma_f32_16x16x32_bf16 v[28:31], v[128:131], v[198:201], v[28:31]
	v_mfma_f32_16x16x32_bf16 v[28:31], v[132:135], v[208:211], v[28:31]
	v_mfma_f32_16x16x32_bf16 v[12:15], v[128:131], v[212:215], v[12:15]
	v_mfma_f32_16x16x32_bf16 v[12:15], v[132:135], v[228:231], v[12:15]
	v_mfma_f32_16x16x32_bf16 v[56:59], v[136:139], v[182:185], v[56:59]
	v_mfma_f32_16x16x32_bf16 v[56:59], v[140:143], v[186:189], v[56:59]
	v_mfma_f32_16x16x32_bf16 v[40:43], v[136:139], v[190:193], v[40:43]
	v_mfma_f32_16x16x32_bf16 v[40:43], v[140:143], v[194:197], v[40:43]
	v_mfma_f32_16x16x32_bf16 v[24:27], v[136:139], v[198:201], v[24:27]
	v_mfma_f32_16x16x32_bf16 v[24:27], v[140:143], v[208:211], v[24:27]
	v_mfma_f32_16x16x32_bf16 v[8:11], v[136:139], v[212:215], v[8:11]
	v_mfma_f32_16x16x32_bf16 v[8:11], v[140:143], v[228:231], v[8:11]
	s_setprio 0
	s_setprio 1
	v_mfma_f32_16x16x32_bf16 v[52:55], v[144:147], v[182:185], v[52:55]
	v_mfma_f32_16x16x32_bf16 v[52:55], v[148:151], v[186:189], v[52:55]
	v_mfma_f32_16x16x32_bf16 v[36:39], v[144:147], v[190:193], v[36:39]
	v_mfma_f32_16x16x32_bf16 v[36:39], v[148:151], v[194:197], v[36:39]
	v_mfma_f32_16x16x32_bf16 v[20:23], v[144:147], v[198:201], v[20:23]
	v_mfma_f32_16x16x32_bf16 v[20:23], v[148:151], v[208:211], v[20:23]
	v_mfma_f32_16x16x32_bf16 v[4:7], v[144:147], v[212:215], v[4:7]
	v_mfma_f32_16x16x32_bf16 v[4:7], v[148:151], v[228:231], v[4:7]
	v_mfma_f32_16x16x32_bf16 v[48:51], v[152:155], v[182:185], v[48:51]
	v_mfma_f32_16x16x32_bf16 v[48:51], v[156:159], v[186:189], v[48:51]
	v_mfma_f32_16x16x32_bf16 v[32:35], v[152:155], v[190:193], v[32:35]
	v_mfma_f32_16x16x32_bf16 v[32:35], v[156:159], v[194:197], v[32:35]
	v_mfma_f32_16x16x32_bf16 v[16:19], v[152:155], v[198:201], v[16:19]
	v_mfma_f32_16x16x32_bf16 v[16:19], v[156:159], v[208:211], v[16:19]
	v_mfma_f32_16x16x32_bf16 v[0:3], v[152:155], v[212:215], v[0:3]
	v_mfma_f32_16x16x32_bf16 v[0:3], v[156:159], v[228:231], v[0:3]
	s_setprio 0
	s_barrier
	s_add_i32 s55, s55, 2
	s_add_u32 s22, s22, 0x100
	s_addc_u32 s23, s23, 0
	s_add_u32 s53, s53, 0x100
	s_addc_u32 s54, s54, 0
	s_cmp_gt_u32 s55, 13
	s_cbranch_scc0 .LBB0_776
	s_and_b64 vcc, exec, s[10:11]
	s_cbranch_vccz .LBB0_779
	s_barrier

.LBB0_890:
	s_add_u32 s18, s0, 0xfffc0080
	s_addc_u32 s19, s1, -1
	s_add_i32 s36, 0, 0x10000
	s_cmp_eq_u32 s50, 12
	s_cselect_b32 s23, s13, s19
	s_cselect_b32 s22, s46, s18
	s_cselect_b32 s19, s11, s49
	s_cselect_b32 s18, s47, s48
	s_add_i32 s51, 0, 0x14000
	v_add_u32_e32 v140, s36, v193
	v_add_u32_e32 v180, s51, v193
	ds_read_b128 v[128:131], v140
	ds_read_b128 v[132:135], v140 offset:1024
	ds_read_b128 v[136:139], v140 offset:2048
	ds_read_b128 v[140:143], v140 offset:3072
	ds_read_b128 v[144:147], v180
	ds_read_b128 v[148:151], v180 offset:1024
	ds_read_b128 v[164:167], v180 offset:2048
	ds_read_b128 v[180:183], v180 offset:3072
	v_lshl_add_u64 v[196:197], s[0:1], 0, v[160:161]
	s_add_i32 m0, s30, 0xc000
	ds_read_b128 v[184:187], v198
	ds_read_b128 v[188:191], v198 offset:1024
	ds_read_b128 v[200:203], v198 offset:2048
	ds_read_b128 v[204:207], v198 offset:3072
	ds_read_b128 v[208:211], v198 offset:4096
	ds_read_b128 v[212:215], v198 offset:5120
	ds_read_b128 v[228:231], v198 offset:6144
	ds_read_b128 v[232:235], v198 offset:7168
	global_load_lds_dwordx4 v[196:197], off
	v_lshl_add_u64 v[196:197], s[0:1], 0, v[162:163]
	s_add_i32 m0, s30, 0xe000
	s_nop 0
	global_load_lds_dwordx4 v[196:197], off
	s_waitcnt vmcnt(8)
	s_waitcnt lgkmcnt(0)
	s_barrier
	s_setprio 1
	s_waitcnt lgkmcnt(0)
	v_mfma_f32_16x16x32_bf16 v[124:127], v[128:131], v[184:187], v[124:127]
	v_mfma_f32_16x16x32_bf16 v[124:127], v[132:135], v[188:191], v[124:127]
	v_mfma_f32_16x16x32_bf16 v[108:111], v[128:131], v[200:203], v[108:111]
	v_mfma_f32_16x16x32_bf16 v[108:111], v[132:135], v[204:207], v[108:111]
	v_mfma_f32_16x16x32_bf16 v[92:95], v[128:131], v[208:211], v[92:95]
	v_mfma_f32_16x16x32_bf16 v[92:95], v[132:135], v[212:215], v[92:95]
	v_mfma_f32_16x16x32_bf16 v[76:79], v[128:131], v[228:231], v[76:79]
	v_mfma_f32_16x16x32_bf16 v[76:79], v[132:135], v[232:235], v[76:79]
	v_mfma_f32_16x16x32_bf16 v[120:123], v[136:139], v[184:187], v[120:123]
	v_mfma_f32_16x16x32_bf16 v[120:123], v[140:143], v[188:191], v[120:123]
	v_mfma_f32_16x16x32_bf16 v[104:107], v[136:139], v[200:203], v[104:107]
	v_mfma_f32_16x16x32_bf16 v[104:107], v[140:143], v[204:207], v[104:107]
	v_mfma_f32_16x16x32_bf16 v[88:91], v[136:139], v[208:211], v[88:91]
	v_mfma_f32_16x16x32_bf16 v[88:91], v[140:143], v[212:215], v[88:91]
	v_mfma_f32_16x16x32_bf16 v[72:75], v[136:139], v[228:231], v[72:75]
	v_mfma_f32_16x16x32_bf16 v[72:75], v[140:143], v[232:235], v[72:75]
	s_setprio 0
	s_setprio 1
	v_mfma_f32_16x16x32_bf16 v[116:119], v[144:147], v[184:187], v[116:119]
	v_mfma_f32_16x16x32_bf16 v[116:119], v[148:151], v[188:191], v[116:119]
	v_mfma_f32_16x16x32_bf16 v[100:103], v[144:147], v[200:203], v[100:103]
	v_mfma_f32_16x16x32_bf16 v[100:103], v[148:151], v[204:207], v[100:103]
	v_mfma_f32_16x16x32_bf16 v[84:87], v[144:147], v[208:211], v[84:87]
	v_mfma_f32_16x16x32_bf16 v[84:87], v[148:151], v[212:215], v[84:87]
	v_mfma_f32_16x16x32_bf16 v[68:71], v[144:147], v[228:231], v[68:71]
	v_mfma_f32_16x16x32_bf16 v[68:71], v[148:151], v[232:235], v[68:71]
	v_mfma_f32_16x16x32_bf16 v[112:115], v[164:167], v[184:187], v[112:115]
	v_mfma_f32_16x16x32_bf16 v[112:115], v[180:183], v[188:191], v[112:115]
	v_mfma_f32_16x16x32_bf16 v[96:99], v[164:167], v[200:203], v[96:99]
	v_mfma_f32_16x16x32_bf16 v[96:99], v[180:183], v[204:207], v[96:99]
	v_mfma_f32_16x16x32_bf16 v[80:83], v[164:167], v[208:211], v[80:83]
	v_mfma_f32_16x16x32_bf16 v[80:83], v[180:183], v[212:215], v[80:83]
	v_mfma_f32_16x16x32_bf16 v[64:67], v[164:167], v[228:231], v[64:67]
	v_mfma_f32_16x16x32_bf16 v[64:67], v[180:183], v[232:235], v[64:67]
	s_setprio 0
	s_barrier
	s_add_i32 s36, s36, s27
	v_lshl_add_u64 v[196:197], s[18:19], 0, v[168:169]
	s_mov_b32 m0, s36
	ds_read_b128 v[184:187], v198 offset:16384
	ds_read_b128 v[188:191], v198 offset:17408
	ds_read_b128 v[200:203], v198 offset:18432
	ds_read_b128 v[204:207], v198 offset:19456
	ds_read_b128 v[208:211], v198 offset:20480
	ds_read_b128 v[212:215], v198 offset:21504
	ds_read_b128 v[228:231], v198 offset:22528
	ds_read_b128 v[232:235], v198 offset:23552
	global_load_lds_dwordx4 v[196:197], off
	s_add_i32 m0, s36, 0x2000
	s_add_u32 s36, s18, 0x40000
	v_lshl_add_u64 v[236:237], s[18:19], 0, v[152:153]
	s_addc_u32 s37, s19, 0
	s_add_i32 s51, s51, s27
	global_load_lds_dwordx4 v[236:237], off
	v_lshl_add_u64 v[238:239], s[36:37], 0, v[168:169]
	s_mov_b32 m0, s51
	v_lshl_add_u64 v[240:241], s[22:23], 0, v[154:155]
	global_load_lds_dwordx4 v[238:239], off
	v_lshl_add_u64 v[238:239], s[36:37], 0, v[152:153]
	s_add_i32 m0, s51, 0x2000
	s_nop 0
	global_load_lds_dwordx4 v[238:239], off
	v_lshl_add_u64 v[238:239], s[22:23], 0, v[156:157]
	s_mov_b32 m0, s30
	s_nop 0
	global_load_lds_dwordx4 v[238:239], off
	s_mov_b32 m0, s31
	s_nop 0
	global_load_lds_dwordx4 v[240:241], off
	s_waitcnt vmcnt(8)
	s_waitcnt lgkmcnt(0)
	s_barrier
	s_setprio 1
	s_waitcnt lgkmcnt(0)
	v_mfma_f32_16x16x32_bf16 v[60:63], v[128:131], v[184:187], v[60:63]
	v_mfma_f32_16x16x32_bf16 v[60:63], v[132:135], v[188:191], v[60:63]
	v_mfma_f32_16x16x32_bf16 v[44:47], v[128:131], v[200:203], v[44:47]
	v_mfma_f32_16x16x32_bf16 v[44:47], v[132:135], v[204:207], v[44:47]
	v_mfma_f32_16x16x32_bf16 v[28:31], v[128:131], v[208:211], v[28:31]
	v_mfma_f32_16x16x32_bf16 v[28:31], v[132:135], v[212:215], v[28:31]
	v_mfma_f32_16x16x32_bf16 v[12:15], v[128:131], v[228:231], v[12:15]
	v_mfma_f32_16x16x32_bf16 v[12:15], v[132:135], v[232:235], v[12:15]
	v_mfma_f32_16x16x32_bf16 v[56:59], v[136:139], v[184:187], v[56:59]
	v_mfma_f32_16x16x32_bf16 v[56:59], v[140:143], v[188:191], v[56:59]
	v_mfma_f32_16x16x32_bf16 v[40:43], v[136:139], v[200:203], v[40:43]
	v_mfma_f32_16x16x32_bf16 v[40:43], v[140:143], v[204:207], v[40:43]
	v_mfma_f32_16x16x32_bf16 v[24:27], v[136:139], v[208:211], v[24:27]
	v_mfma_f32_16x16x32_bf16 v[24:27], v[140:143], v[212:215], v[24:27]
	v_mfma_f32_16x16x32_bf16 v[8:11], v[136:139], v[228:231], v[8:11]
	v_mfma_f32_16x16x32_bf16 v[8:11], v[140:143], v[232:235], v[8:11]
	s_setprio 0
	s_setprio 1
	v_mfma_f32_16x16x32_bf16 v[52:55], v[144:147], v[184:187], v[52:55]
	v_mfma_f32_16x16x32_bf16 v[52:55], v[148:151], v[188:191], v[52:55]
	v_mfma_f32_16x16x32_bf16 v[36:39], v[144:147], v[200:203], v[36:39]
	v_mfma_f32_16x16x32_bf16 v[36:39], v[148:151], v[204:207], v[36:39]
	v_mfma_f32_16x16x32_bf16 v[20:23], v[144:147], v[208:211], v[20:23]
	v_mfma_f32_16x16x32_bf16 v[20:23], v[148:151], v[212:215], v[20:23]
	v_mfma_f32_16x16x32_bf16 v[4:7], v[144:147], v[228:231], v[4:7]
	v_mfma_f32_16x16x32_bf16 v[4:7], v[148:151], v[232:235], v[4:7]
	v_mfma_f32_16x16x32_bf16 v[48:51], v[164:167], v[184:187], v[48:51]
	v_mfma_f32_16x16x32_bf16 v[48:51], v[180:183], v[188:191], v[48:51]
	v_mfma_f32_16x16x32_bf16 v[32:35], v[164:167], v[200:203], v[32:35]
	v_mfma_f32_16x16x32_bf16 v[32:35], v[180:183], v[204:207], v[32:35]
	v_mfma_f32_16x16x32_bf16 v[16:19], v[164:167], v[208:211], v[16:19]
	v_mfma_f32_16x16x32_bf16 v[16:19], v[180:183], v[212:215], v[16:19]
	v_mfma_f32_16x16x32_bf16 v[0:3], v[164:167], v[228:231], v[0:3]
	v_mfma_f32_16x16x32_bf16 v[0:3], v[180:183], v[232:235], v[0:3]
	s_setprio 0
	s_barrier
	s_add_i32 s36, 0, 0x18000
	s_add_i32 s37, 0, 0x1c000
	v_add_u32_e32 v140, s36, v193
	v_add_u32_e32 v180, s37, v193
	ds_read_b128 v[128:131], v140
	ds_read_b128 v[132:135], v140 offset:1024
	ds_read_b128 v[136:139], v140 offset:2048
	ds_read_b128 v[140:143], v140 offset:3072
	ds_read_b128 v[144:147], v180
	ds_read_b128 v[148:151], v180 offset:1024
	ds_read_b128 v[164:167], v180 offset:2048
	ds_read_b128 v[180:183], v180 offset:3072
	s_add_u32 s22, s22, 0x40000
	s_addc_u32 s23, s23, 0
	s_mov_b32 m0, s34
	v_lshl_add_u64 v[242:243], s[22:23], 0, v[156:157]
	ds_read_b128 v[184:187], v198 offset:32768
	ds_read_b128 v[188:191], v198 offset:33792
	ds_read_b128 v[200:203], v198 offset:34816
	ds_read_b128 v[204:207], v198 offset:35840
	ds_read_b128 v[208:211], v198 offset:36864
	ds_read_b128 v[212:215], v198 offset:37888
	ds_read_b128 v[228:231], v198 offset:38912
	ds_read_b128 v[232:235], v198 offset:39936
	global_load_lds_dwordx4 v[242:243], off
	v_lshl_add_u64 v[242:243], s[22:23], 0, v[154:155]
	s_mov_b32 m0, s35
	s_nop 0
	global_load_lds_dwordx4 v[242:243], off
	s_waitcnt vmcnt(8)
	s_waitcnt lgkmcnt(0)
	s_barrier
	s_setprio 1
	s_waitcnt lgkmcnt(0)
	v_mfma_f32_16x16x32_bf16 v[124:127], v[128:131], v[184:187], v[124:127]
	v_mfma_f32_16x16x32_bf16 v[124:127], v[132:135], v[188:191], v[124:127]
	v_mfma_f32_16x16x32_bf16 v[108:111], v[128:131], v[200:203], v[108:111]
	v_mfma_f32_16x16x32_bf16 v[108:111], v[132:135], v[204:207], v[108:111]
	v_mfma_f32_16x16x32_bf16 v[92:95], v[128:131], v[208:211], v[92:95]
	v_mfma_f32_16x16x32_bf16 v[92:95], v[132:135], v[212:215], v[92:95]
	v_mfma_f32_16x16x32_bf16 v[76:79], v[128:131], v[228:231], v[76:79]
	v_mfma_f32_16x16x32_bf16 v[76:79], v[132:135], v[232:235], v[76:79]
	v_mfma_f32_16x16x32_bf16 v[120:123], v[136:139], v[184:187], v[120:123]
	v_mfma_f32_16x16x32_bf16 v[120:123], v[140:143], v[188:191], v[120:123]
	v_mfma_f32_16x16x32_bf16 v[104:107], v[136:139], v[200:203], v[104:107]
	v_mfma_f32_16x16x32_bf16 v[104:107], v[140:143], v[204:207], v[104:107]
	v_mfma_f32_16x16x32_bf16 v[88:91], v[136:139], v[208:211], v[88:91]
	v_mfma_f32_16x16x32_bf16 v[88:91], v[140:143], v[212:215], v[88:91]
	v_mfma_f32_16x16x32_bf16 v[72:75], v[136:139], v[228:231], v[72:75]
	v_mfma_f32_16x16x32_bf16 v[72:75], v[140:143], v[232:235], v[72:75]
	s_setprio 0
	s_setprio 1
	v_mfma_f32_16x16x32_bf16 v[116:119], v[144:147], v[184:187], v[116:119]
	v_mfma_f32_16x16x32_bf16 v[116:119], v[148:151], v[188:191], v[116:119]
	v_mfma_f32_16x16x32_bf16 v[100:103], v[144:147], v[200:203], v[100:103]
	v_mfma_f32_16x16x32_bf16 v[100:103], v[148:151], v[204:207], v[100:103]
	v_mfma_f32_16x16x32_bf16 v[84:87], v[144:147], v[208:211], v[84:87]
	v_mfma_f32_16x16x32_bf16 v[84:87], v[148:151], v[212:215], v[84:87]
	v_mfma_f32_16x16x32_bf16 v[68:71], v[144:147], v[228:231], v[68:71]
	v_mfma_f32_16x16x32_bf16 v[68:71], v[148:151], v[232:235], v[68:71]
	v_mfma_f32_16x16x32_bf16 v[112:115], v[164:167], v[184:187], v[112:115]
	v_mfma_f32_16x16x32_bf16 v[112:115], v[180:183], v[188:191], v[112:115]
	v_mfma_f32_16x16x32_bf16 v[96:99], v[164:167], v[200:203], v[96:99]
	v_mfma_f32_16x16x32_bf16 v[96:99], v[180:183], v[204:207], v[96:99]
	v_mfma_f32_16x16x32_bf16 v[80:83], v[164:167], v[208:211], v[80:83]
	v_mfma_f32_16x16x32_bf16 v[80:83], v[180:183], v[212:215], v[80:83]
	v_mfma_f32_16x16x32_bf16 v[64:67], v[164:167], v[228:231], v[64:67]
	v_mfma_f32_16x16x32_bf16 v[64:67], v[180:183], v[232:235], v[64:67]
	s_setprio 0
	s_barrier
	s_add_i32 s22, s36, s27
	v_lshl_add_u64 v[196:197], v[196:197], 0, s[20:21]
	s_mov_b32 m0, s22
	ds_read_b128 v[184:187], v198 offset:49152
	ds_read_b128 v[188:191], v198 offset:50176
	ds_read_b128 v[200:203], v198 offset:51200
	ds_read_b128 v[204:207], v198 offset:52224
	ds_read_b128 v[208:211], v198 offset:53248
	ds_read_b128 v[212:215], v198 offset:54272
	ds_read_b128 v[228:231], v198 offset:55296
	ds_read_b128 v[232:235], v198 offset:56320
	global_load_lds_dwordx4 v[196:197], off
	s_add_i32 m0, s22, 0x2000
	s_add_u32 s18, s18, 0x40080
	v_lshl_add_u64 v[196:197], v[236:237], 0, s[20:21]
	s_addc_u32 s19, s19, 0
	s_add_i32 s22, s37, s27
	global_load_lds_dwordx4 v[196:197], off
	v_lshl_add_u64 v[196:197], s[18:19], 0, v[168:169]
	s_mov_b32 m0, s22
	s_nop 0
	global_load_lds_dwordx4 v[196:197], off
	v_lshl_add_u64 v[196:197], s[18:19], 0, v[152:153]
	s_add_i32 m0, s22, 0x2000
	s_nop 0
	global_load_lds_dwordx4 v[196:197], off
	v_lshl_add_u64 v[196:197], v[238:239], 0, s[20:21]
	s_mov_b32 m0, s24
	s_nop 0
	global_load_lds_dwordx4 v[196:197], off
	v_lshl_add_u64 v[196:197], v[240:241], 0, s[20:21]
	s_mov_b32 m0, s42
	s_nop 0
	global_load_lds_dwordx4 v[196:197], off
	s_waitcnt vmcnt(8)
	s_waitcnt lgkmcnt(0)
	s_barrier
	s_setprio 1
	s_waitcnt lgkmcnt(0)
	v_mfma_f32_16x16x32_bf16 v[60:63], v[128:131], v[184:187], v[60:63]
	v_mfma_f32_16x16x32_bf16 v[60:63], v[132:135], v[188:191], v[60:63]
	v_mfma_f32_16x16x32_bf16 v[44:47], v[128:131], v[200:203], v[44:47]
	v_mfma_f32_16x16x32_bf16 v[44:47], v[132:135], v[204:207], v[44:47]
	v_mfma_f32_16x16x32_bf16 v[28:31], v[128:131], v[208:211], v[28:31]
	v_mfma_f32_16x16x32_bf16 v[28:31], v[132:135], v[212:215], v[28:31]
	v_mfma_f32_16x16x32_bf16 v[12:15], v[128:131], v[228:231], v[12:15]
	v_mfma_f32_16x16x32_bf16 v[12:15], v[132:135], v[232:235], v[12:15]
	v_mfma_f32_16x16x32_bf16 v[56:59], v[136:139], v[184:187], v[56:59]
	v_mfma_f32_16x16x32_bf16 v[56:59], v[140:143], v[188:191], v[56:59]
	v_mfma_f32_16x16x32_bf16 v[40:43], v[136:139], v[200:203], v[40:43]
	v_mfma_f32_16x16x32_bf16 v[40:43], v[140:143], v[204:207], v[40:43]
	v_mfma_f32_16x16x32_bf16 v[24:27], v[136:139], v[208:211], v[24:27]
	v_mfma_f32_16x16x32_bf16 v[24:27], v[140:143], v[212:215], v[24:27]
	v_mfma_f32_16x16x32_bf16 v[8:11], v[136:139], v[228:231], v[8:11]
	v_mfma_f32_16x16x32_bf16 v[8:11], v[140:143], v[232:235], v[8:11]
	s_setprio 0
	s_setprio 1
	v_mfma_f32_16x16x32_bf16 v[52:55], v[144:147], v[184:187], v[52:55]
	v_mfma_f32_16x16x32_bf16 v[52:55], v[148:151], v[188:191], v[52:55]
	v_mfma_f32_16x16x32_bf16 v[36:39], v[144:147], v[200:203], v[36:39]
	v_mfma_f32_16x16x32_bf16 v[36:39], v[148:151], v[204:207], v[36:39]
	v_mfma_f32_16x16x32_bf16 v[20:23], v[144:147], v[208:211], v[20:23]
	v_mfma_f32_16x16x32_bf16 v[20:23], v[148:151], v[212:215], v[20:23]
	v_mfma_f32_16x16x32_bf16 v[4:7], v[144:147], v[228:231], v[4:7]
	v_mfma_f32_16x16x32_bf16 v[4:7], v[148:151], v[232:235], v[4:7]
	v_mfma_f32_16x16x32_bf16 v[48:51], v[164:167], v[184:187], v[48:51]
	v_mfma_f32_16x16x32_bf16 v[48:51], v[180:183], v[188:191], v[48:51]
	v_mfma_f32_16x16x32_bf16 v[32:35], v[164:167], v[200:203], v[32:35]
	v_mfma_f32_16x16x32_bf16 v[32:35], v[180:183], v[204:207], v[32:35]
	v_mfma_f32_16x16x32_bf16 v[16:19], v[164:167], v[208:211], v[16:19]
	v_mfma_f32_16x16x32_bf16 v[16:19], v[180:183], v[212:215], v[16:19]
	v_mfma_f32_16x16x32_bf16 v[0:3], v[164:167], v[228:231], v[0:3]
	v_mfma_f32_16x16x32_bf16 v[0:3], v[180:183], v[232:235], v[0:3]
	s_setprio 0
	s_barrier
	s_add_i32 s50, s50, 2
	s_add_u32 s0, s0, 0x100
	s_addc_u32 s1, s1, 0
	s_add_u32 s48, s48, 0x100
	s_addc_u32 s49, s49, 0
	s_cmp_gt_u32 s50, 13
	s_cbranch_scc0 .LBB0_890
	s_and_b64 vcc, exec, s[8:9]
	s_cbranch_vccz .LBB0_893
	s_barrier

.LBB0_986:
	s_add_u32 s34, s8, 0xfff00080
	s_addc_u32 s35, s9, -1
	s_add_i32 s36, 0, 0x10000
	s_cmp_eq_u32 s57, 60
	s_cselect_b32 s41, s23, s35
	s_cselect_b32 s40, s53, s34
	s_cselect_b32 s35, s19, s56
	s_cselect_b32 s34, s54, s55
	s_add_i32 s58, 0, 0x14000
	v_add_u32_e32 v140, s36, v228
	v_add_u32_e32 v156, s58, v228
	ds_read_b128 v[128:131], v140
	ds_read_b128 v[132:135], v140 offset:1024
	ds_read_b128 v[136:139], v140 offset:2048
	ds_read_b128 v[140:143], v140 offset:3072
	ds_read_b128 v[144:147], v156
	ds_read_b128 v[148:151], v156 offset:1024
	ds_read_b128 v[152:155], v156 offset:2048
	ds_read_b128 v[156:159], v156 offset:3072
	v_lshl_add_u64 v[214:215], s[8:9], 0, v[186:187]
	s_add_i32 m0, s44, 0xc000
	ds_read_b128 v[160:163], v230
	ds_read_b128 v[164:167], v230 offset:1024
	ds_read_b128 v[190:193], v230 offset:2048
	ds_read_b128 v[194:197], v230 offset:3072
	ds_read_b128 v[198:201], v230 offset:4096
	ds_read_b128 v[202:205], v230 offset:5120
	ds_read_b128 v[206:209], v230 offset:6144
	ds_read_b128 v[210:213], v230 offset:7168
	global_load_lds_dwordx4 v[214:215], off
	v_lshl_add_u64 v[214:215], s[8:9], 0, v[188:189]
	s_add_i32 m0, s44, 0xe000
	s_nop 0
	global_load_lds_dwordx4 v[214:215], off
	s_waitcnt vmcnt(8)
	s_waitcnt lgkmcnt(0)
	s_barrier
	s_setprio 1
	s_waitcnt lgkmcnt(0)
	v_mfma_f32_16x16x32_bf16 v[124:127], v[128:131], v[160:163], v[124:127]
	v_mfma_f32_16x16x32_bf16 v[124:127], v[132:135], v[164:167], v[124:127]
	v_mfma_f32_16x16x32_bf16 v[108:111], v[128:131], v[190:193], v[108:111]
	v_mfma_f32_16x16x32_bf16 v[108:111], v[132:135], v[194:197], v[108:111]
	v_mfma_f32_16x16x32_bf16 v[92:95], v[128:131], v[198:201], v[92:95]
	v_mfma_f32_16x16x32_bf16 v[92:95], v[132:135], v[202:205], v[92:95]
	v_mfma_f32_16x16x32_bf16 v[76:79], v[128:131], v[206:209], v[76:79]
	v_mfma_f32_16x16x32_bf16 v[76:79], v[132:135], v[210:213], v[76:79]
	v_mfma_f32_16x16x32_bf16 v[120:123], v[136:139], v[160:163], v[120:123]
	v_mfma_f32_16x16x32_bf16 v[120:123], v[140:143], v[164:167], v[120:123]
	v_mfma_f32_16x16x32_bf16 v[104:107], v[136:139], v[190:193], v[104:107]
	v_mfma_f32_16x16x32_bf16 v[104:107], v[140:143], v[194:197], v[104:107]
	v_mfma_f32_16x16x32_bf16 v[88:91], v[136:139], v[198:201], v[88:91]
	v_mfma_f32_16x16x32_bf16 v[88:91], v[140:143], v[202:205], v[88:91]
	v_mfma_f32_16x16x32_bf16 v[72:75], v[136:139], v[206:209], v[72:75]
	v_mfma_f32_16x16x32_bf16 v[72:75], v[140:143], v[210:213], v[72:75]
	s_setprio 0
	s_setprio 1
	v_mfma_f32_16x16x32_bf16 v[116:119], v[144:147], v[160:163], v[116:119]
	v_mfma_f32_16x16x32_bf16 v[116:119], v[148:151], v[164:167], v[116:119]
	v_mfma_f32_16x16x32_bf16 v[100:103], v[144:147], v[190:193], v[100:103]
	v_mfma_f32_16x16x32_bf16 v[100:103], v[148:151], v[194:197], v[100:103]
	v_mfma_f32_16x16x32_bf16 v[84:87], v[144:147], v[198:201], v[84:87]
	v_mfma_f32_16x16x32_bf16 v[84:87], v[148:151], v[202:205], v[84:87]
	v_mfma_f32_16x16x32_bf16 v[68:71], v[144:147], v[206:209], v[68:71]
	v_mfma_f32_16x16x32_bf16 v[68:71], v[148:151], v[210:213], v[68:71]
	v_mfma_f32_16x16x32_bf16 v[112:115], v[152:155], v[160:163], v[112:115]
	v_mfma_f32_16x16x32_bf16 v[112:115], v[156:159], v[164:167], v[112:115]
	v_mfma_f32_16x16x32_bf16 v[96:99], v[152:155], v[190:193], v[96:99]
	v_mfma_f32_16x16x32_bf16 v[96:99], v[156:159], v[194:197], v[96:99]
	v_mfma_f32_16x16x32_bf16 v[80:83], v[152:155], v[198:201], v[80:83]
	v_mfma_f32_16x16x32_bf16 v[80:83], v[156:159], v[202:205], v[80:83]
	v_mfma_f32_16x16x32_bf16 v[64:67], v[152:155], v[206:209], v[64:67]
	v_mfma_f32_16x16x32_bf16 v[64:67], v[156:159], v[210:213], v[64:67]
	s_setprio 0
	s_barrier
	s_add_i32 s36, s36, s43
	v_lshl_add_u64 v[214:215], s[34:35], 0, v[168:169]
	s_mov_b32 m0, s36
	ds_read_b128 v[160:163], v230 offset:16384
	ds_read_b128 v[164:167], v230 offset:17408
	ds_read_b128 v[190:193], v230 offset:18432
	ds_read_b128 v[194:197], v230 offset:19456
	ds_read_b128 v[198:201], v230 offset:20480
	ds_read_b128 v[202:205], v230 offset:21504
	ds_read_b128 v[206:209], v230 offset:22528
	ds_read_b128 v[210:213], v230 offset:23552
	global_load_lds_dwordx4 v[214:215], off
	s_add_i32 m0, s36, 0x2000
	s_add_u32 s36, s34, 0x100000
	v_lshl_add_u64 v[232:233], s[34:35], 0, v[180:181]
	s_addc_u32 s37, s35, 0
	s_add_i32 s58, s58, s43
	global_load_lds_dwordx4 v[232:233], off
	v_lshl_add_u64 v[234:235], s[36:37], 0, v[168:169]
	s_mov_b32 m0, s58
	v_lshl_add_u64 v[236:237], s[40:41], 0, v[182:183]
	global_load_lds_dwordx4 v[234:235], off
	v_lshl_add_u64 v[234:235], s[36:37], 0, v[180:181]
	s_add_i32 m0, s58, 0x2000
	s_nop 0
	global_load_lds_dwordx4 v[234:235], off
	v_lshl_add_u64 v[234:235], s[40:41], 0, v[184:185]
	s_mov_b32 m0, s44
	s_nop 0
	global_load_lds_dwordx4 v[234:235], off
	s_mov_b32 m0, s45
	s_nop 0
	global_load_lds_dwordx4 v[236:237], off
	s_waitcnt vmcnt(8)
	s_waitcnt lgkmcnt(0)
	s_barrier
	s_setprio 1
	s_waitcnt lgkmcnt(0)
	v_mfma_f32_16x16x32_bf16 v[60:63], v[128:131], v[160:163], v[60:63]
	v_mfma_f32_16x16x32_bf16 v[60:63], v[132:135], v[164:167], v[60:63]
	v_mfma_f32_16x16x32_bf16 v[44:47], v[128:131], v[190:193], v[44:47]
	v_mfma_f32_16x16x32_bf16 v[44:47], v[132:135], v[194:197], v[44:47]
	v_mfma_f32_16x16x32_bf16 v[28:31], v[128:131], v[198:201], v[28:31]
	v_mfma_f32_16x16x32_bf16 v[28:31], v[132:135], v[202:205], v[28:31]
	v_mfma_f32_16x16x32_bf16 v[12:15], v[128:131], v[206:209], v[12:15]
	v_mfma_f32_16x16x32_bf16 v[12:15], v[132:135], v[210:213], v[12:15]
	v_mfma_f32_16x16x32_bf16 v[56:59], v[136:139], v[160:163], v[56:59]
	v_mfma_f32_16x16x32_bf16 v[56:59], v[140:143], v[164:167], v[56:59]
	v_mfma_f32_16x16x32_bf16 v[40:43], v[136:139], v[190:193], v[40:43]
	v_mfma_f32_16x16x32_bf16 v[40:43], v[140:143], v[194:197], v[40:43]
	v_mfma_f32_16x16x32_bf16 v[24:27], v[136:139], v[198:201], v[24:27]
	v_mfma_f32_16x16x32_bf16 v[24:27], v[140:143], v[202:205], v[24:27]
	v_mfma_f32_16x16x32_bf16 v[8:11], v[136:139], v[206:209], v[8:11]
	v_mfma_f32_16x16x32_bf16 v[8:11], v[140:143], v[210:213], v[8:11]
	s_setprio 0
	s_setprio 1
	v_mfma_f32_16x16x32_bf16 v[52:55], v[144:147], v[160:163], v[52:55]
	v_mfma_f32_16x16x32_bf16 v[52:55], v[148:151], v[164:167], v[52:55]
	v_mfma_f32_16x16x32_bf16 v[36:39], v[144:147], v[190:193], v[36:39]
	v_mfma_f32_16x16x32_bf16 v[36:39], v[148:151], v[194:197], v[36:39]
	v_mfma_f32_16x16x32_bf16 v[20:23], v[144:147], v[198:201], v[20:23]
	v_mfma_f32_16x16x32_bf16 v[20:23], v[148:151], v[202:205], v[20:23]
	v_mfma_f32_16x16x32_bf16 v[4:7], v[144:147], v[206:209], v[4:7]
	v_mfma_f32_16x16x32_bf16 v[4:7], v[148:151], v[210:213], v[4:7]
	v_mfma_f32_16x16x32_bf16 v[48:51], v[152:155], v[160:163], v[48:51]
	v_mfma_f32_16x16x32_bf16 v[48:51], v[156:159], v[164:167], v[48:51]
	v_mfma_f32_16x16x32_bf16 v[32:35], v[152:155], v[190:193], v[32:35]
	v_mfma_f32_16x16x32_bf16 v[32:35], v[156:159], v[194:197], v[32:35]
	v_mfma_f32_16x16x32_bf16 v[16:19], v[152:155], v[198:201], v[16:19]
	v_mfma_f32_16x16x32_bf16 v[16:19], v[156:159], v[202:205], v[16:19]
	v_mfma_f32_16x16x32_bf16 v[0:3], v[152:155], v[206:209], v[0:3]
	v_mfma_f32_16x16x32_bf16 v[0:3], v[156:159], v[210:213], v[0:3]
	s_setprio 0
	s_barrier
	s_add_i32 s58, 0, 0x18000
	s_add_i32 s59, 0, 0x1c000
	v_add_u32_e32 v140, s58, v228
	v_add_u32_e32 v156, s59, v228
	ds_read_b128 v[128:131], v140
	ds_read_b128 v[132:135], v140 offset:1024
	ds_read_b128 v[136:139], v140 offset:2048
	ds_read_b128 v[140:143], v140 offset:3072
	ds_read_b128 v[144:147], v156
	ds_read_b128 v[148:151], v156 offset:1024
	ds_read_b128 v[152:155], v156 offset:2048
	ds_read_b128 v[156:159], v156 offset:3072
	s_add_u32 s36, s40, 0x100000
	s_addc_u32 s37, s41, 0
	s_mov_b32 m0, s46
	v_lshl_add_u64 v[238:239], s[36:37], 0, v[184:185]
	ds_read_b128 v[160:163], v230 offset:32768
	ds_read_b128 v[164:167], v230 offset:33792
	ds_read_b128 v[190:193], v230 offset:34816
	ds_read_b128 v[194:197], v230 offset:35840
	ds_read_b128 v[198:201], v230 offset:36864
	ds_read_b128 v[202:205], v230 offset:37888
	ds_read_b128 v[206:209], v230 offset:38912
	ds_read_b128 v[210:213], v230 offset:39936
	global_load_lds_dwordx4 v[238:239], off
	v_lshl_add_u64 v[238:239], s[36:37], 0, v[182:183]
	s_mov_b32 m0, s47
	s_nop 0
	global_load_lds_dwordx4 v[238:239], off
	s_waitcnt vmcnt(8)
	s_waitcnt lgkmcnt(0)
	s_barrier
	s_setprio 1
	s_waitcnt lgkmcnt(0)
	v_mfma_f32_16x16x32_bf16 v[124:127], v[128:131], v[160:163], v[124:127]
	v_mfma_f32_16x16x32_bf16 v[124:127], v[132:135], v[164:167], v[124:127]
	v_mfma_f32_16x16x32_bf16 v[108:111], v[128:131], v[190:193], v[108:111]
	v_mfma_f32_16x16x32_bf16 v[108:111], v[132:135], v[194:197], v[108:111]
	v_mfma_f32_16x16x32_bf16 v[92:95], v[128:131], v[198:201], v[92:95]
	v_mfma_f32_16x16x32_bf16 v[92:95], v[132:135], v[202:205], v[92:95]
	v_mfma_f32_16x16x32_bf16 v[76:79], v[128:131], v[206:209], v[76:79]
	v_mfma_f32_16x16x32_bf16 v[76:79], v[132:135], v[210:213], v[76:79]
	v_mfma_f32_16x16x32_bf16 v[120:123], v[136:139], v[160:163], v[120:123]
	v_mfma_f32_16x16x32_bf16 v[120:123], v[140:143], v[164:167], v[120:123]
	v_mfma_f32_16x16x32_bf16 v[104:107], v[136:139], v[190:193], v[104:107]
	v_mfma_f32_16x16x32_bf16 v[104:107], v[140:143], v[194:197], v[104:107]
	v_mfma_f32_16x16x32_bf16 v[88:91], v[136:139], v[198:201], v[88:91]
	v_mfma_f32_16x16x32_bf16 v[88:91], v[140:143], v[202:205], v[88:91]
	v_mfma_f32_16x16x32_bf16 v[72:75], v[136:139], v[206:209], v[72:75]
	v_mfma_f32_16x16x32_bf16 v[72:75], v[140:143], v[210:213], v[72:75]
	s_setprio 0
	s_setprio 1
	v_mfma_f32_16x16x32_bf16 v[116:119], v[144:147], v[160:163], v[116:119]
	v_mfma_f32_16x16x32_bf16 v[116:119], v[148:151], v[164:167], v[116:119]
	v_mfma_f32_16x16x32_bf16 v[100:103], v[144:147], v[190:193], v[100:103]
	v_mfma_f32_16x16x32_bf16 v[100:103], v[148:151], v[194:197], v[100:103]
	v_mfma_f32_16x16x32_bf16 v[84:87], v[144:147], v[198:201], v[84:87]
	v_mfma_f32_16x16x32_bf16 v[84:87], v[148:151], v[202:205], v[84:87]
	v_mfma_f32_16x16x32_bf16 v[68:71], v[144:147], v[206:209], v[68:71]
	v_mfma_f32_16x16x32_bf16 v[68:71], v[148:151], v[210:213], v[68:71]
	v_mfma_f32_16x16x32_bf16 v[112:115], v[152:155], v[160:163], v[112:115]
	v_mfma_f32_16x16x32_bf16 v[112:115], v[156:159], v[164:167], v[112:115]
	v_mfma_f32_16x16x32_bf16 v[96:99], v[152:155], v[190:193], v[96:99]
	v_mfma_f32_16x16x32_bf16 v[96:99], v[156:159], v[194:197], v[96:99]
	v_mfma_f32_16x16x32_bf16 v[80:83], v[152:155], v[198:201], v[80:83]
	v_mfma_f32_16x16x32_bf16 v[80:83], v[156:159], v[202:205], v[80:83]
	v_mfma_f32_16x16x32_bf16 v[64:67], v[152:155], v[206:209], v[64:67]
	v_mfma_f32_16x16x32_bf16 v[64:67], v[156:159], v[210:213], v[64:67]
	s_setprio 0
	s_barrier
	s_add_i32 s36, s58, s43
	v_lshl_add_u64 v[214:215], v[214:215], 0, s[20:21]
	s_mov_b32 m0, s36
	ds_read_b128 v[160:163], v230 offset:49152
	ds_read_b128 v[164:167], v230 offset:50176
	ds_read_b128 v[190:193], v230 offset:51200
	ds_read_b128 v[194:197], v230 offset:52224
	ds_read_b128 v[198:201], v230 offset:53248
	ds_read_b128 v[202:205], v230 offset:54272
	ds_read_b128 v[206:209], v230 offset:55296
	ds_read_b128 v[210:213], v230 offset:56320
	global_load_lds_dwordx4 v[214:215], off
	s_add_i32 m0, s36, 0x2000
	s_add_u32 s34, s34, 0x100080
	v_lshl_add_u64 v[214:215], v[232:233], 0, s[20:21]
	s_addc_u32 s35, s35, 0
	s_add_i32 s36, s59, s43
	global_load_lds_dwordx4 v[214:215], off
	v_lshl_add_u64 v[214:215], s[34:35], 0, v[168:169]
	s_mov_b32 m0, s36
	s_nop 0
	global_load_lds_dwordx4 v[214:215], off
	v_lshl_add_u64 v[214:215], s[34:35], 0, v[180:181]
	s_add_i32 m0, s36, 0x2000
	s_nop 0
	global_load_lds_dwordx4 v[214:215], off
	v_lshl_add_u64 v[214:215], v[234:235], 0, s[20:21]
	s_mov_b32 m0, s50
	s_nop 0
	global_load_lds_dwordx4 v[214:215], off
	v_lshl_add_u64 v[214:215], v[236:237], 0, s[20:21]
	s_mov_b32 m0, s51
	s_nop 0
	global_load_lds_dwordx4 v[214:215], off
	s_waitcnt vmcnt(8)
	s_waitcnt lgkmcnt(0)
	s_barrier
	s_setprio 1
	s_waitcnt lgkmcnt(0)
	v_mfma_f32_16x16x32_bf16 v[60:63], v[128:131], v[160:163], v[60:63]
	v_mfma_f32_16x16x32_bf16 v[60:63], v[132:135], v[164:167], v[60:63]
	v_mfma_f32_16x16x32_bf16 v[44:47], v[128:131], v[190:193], v[44:47]
	v_mfma_f32_16x16x32_bf16 v[44:47], v[132:135], v[194:197], v[44:47]
	v_mfma_f32_16x16x32_bf16 v[28:31], v[128:131], v[198:201], v[28:31]
	v_mfma_f32_16x16x32_bf16 v[28:31], v[132:135], v[202:205], v[28:31]
	v_mfma_f32_16x16x32_bf16 v[12:15], v[128:131], v[206:209], v[12:15]
	v_mfma_f32_16x16x32_bf16 v[12:15], v[132:135], v[210:213], v[12:15]
	v_mfma_f32_16x16x32_bf16 v[56:59], v[136:139], v[160:163], v[56:59]
	v_mfma_f32_16x16x32_bf16 v[56:59], v[140:143], v[164:167], v[56:59]
	v_mfma_f32_16x16x32_bf16 v[40:43], v[136:139], v[190:193], v[40:43]
	v_mfma_f32_16x16x32_bf16 v[40:43], v[140:143], v[194:197], v[40:43]
	v_mfma_f32_16x16x32_bf16 v[24:27], v[136:139], v[198:201], v[24:27]
	v_mfma_f32_16x16x32_bf16 v[24:27], v[140:143], v[202:205], v[24:27]
	v_mfma_f32_16x16x32_bf16 v[8:11], v[136:139], v[206:209], v[8:11]
	v_mfma_f32_16x16x32_bf16 v[8:11], v[140:143], v[210:213], v[8:11]
	s_setprio 0
	s_setprio 1
	v_mfma_f32_16x16x32_bf16 v[52:55], v[144:147], v[160:163], v[52:55]
	v_mfma_f32_16x16x32_bf16 v[52:55], v[148:151], v[164:167], v[52:55]
	v_mfma_f32_16x16x32_bf16 v[36:39], v[144:147], v[190:193], v[36:39]
	v_mfma_f32_16x16x32_bf16 v[36:39], v[148:151], v[194:197], v[36:39]
	v_mfma_f32_16x16x32_bf16 v[20:23], v[144:147], v[198:201], v[20:23]
	v_mfma_f32_16x16x32_bf16 v[20:23], v[148:151], v[202:205], v[20:23]
	v_mfma_f32_16x16x32_bf16 v[4:7], v[144:147], v[206:209], v[4:7]
	v_mfma_f32_16x16x32_bf16 v[4:7], v[148:151], v[210:213], v[4:7]
	v_mfma_f32_16x16x32_bf16 v[48:51], v[152:155], v[160:163], v[48:51]
	v_mfma_f32_16x16x32_bf16 v[48:51], v[156:159], v[164:167], v[48:51]
	v_mfma_f32_16x16x32_bf16 v[32:35], v[152:155], v[190:193], v[32:35]
	v_mfma_f32_16x16x32_bf16 v[32:35], v[156:159], v[194:197], v[32:35]
	v_mfma_f32_16x16x32_bf16 v[16:19], v[152:155], v[198:201], v[16:19]
	v_mfma_f32_16x16x32_bf16 v[16:19], v[156:159], v[202:205], v[16:19]
	v_mfma_f32_16x16x32_bf16 v[0:3], v[152:155], v[206:209], v[0:3]
	v_mfma_f32_16x16x32_bf16 v[0:3], v[156:159], v[210:213], v[0:3]
	s_setprio 0
	s_barrier
	s_add_i32 s57, s57, 2
	s_add_u32 s8, s8, 0x100
	s_addc_u32 s9, s9, 0
	s_add_u32 s55, s55, 0x100
	s_addc_u32 s56, s56, 0
	s_cmp_gt_u32 s57, 61
	s_cbranch_scc0 .LBB0_986
	s_and_b64 vcc, exec, s[12:13]
	s_cbranch_vccz .LBB0_989
	s_barrier
